# dilated attention: q block also loaded row-contiguously and transposed through LDS (was 32-row x 32-B gather)
# speedup vs baseline: 1.0226x; 1.0036x over previous
.LBB0_510:
	s_ashr_i32 s8, s54, 9
	s_mul_hi_i32 s10, s8, 0x55555556
	s_lshr_b32 s11, s10, 31
	s_add_i32 s10, s10, s11
	s_mul_i32 s11, s10, 3
	s_sub_i32 s50, s8, s11
	s_mul_hi_i32 s8, s8, 0x2aaaaaab
	s_and_b32 s57, s10, 3
	s_lshr_b32 s10, s8, 31
	s_ashr_i32 s8, s8, 1
	s_lshl_b32 s55, s50, 1
	s_add_i32 s8, s8, s10
	s_lshr_b32 s10, 0x200, s55
	s_and_b32 s9, s54, 0x1ff
	s_add_i32 s10, s10, -1
	s_sub_i32 s11, 9, s55
	s_and_b32 s18, s10, s9
	s_lshr_b32 s72, s9, s11
	s_lshl_b32 s56, s18, 5
	s_ashr_i32 s9, s8, 31
	s_lshl_b64 s[52:53], s[8:9], 14
	v_or_b32_e32 v0, s56, v181
	v_lshlrev_b64 v[186:187], s55, v[0:1]
	s_or_b32 s10, s52, s72
	s_mov_b32 s11, s53
	v_lshl_add_u64 v[2:3], v[186:187], 0, s[10:11]
	v_mov_b64_e32 v[4:5], s[26:27]
	v_mad_u64_u32 v[4:5], s[16:17], v2, s83, v[4:5]
	v_mov_b32_e32 v0, v5
	v_mad_u64_u32 v[2:3], s[16:17], v3, s83, v[0:1]
	s_add_i32 s16, s33, s57
	s_nop 0
	v_cvt_f32_u32_e32 v8, s16
	s_mul_i32 s8, s57, 0x480
	s_lshl_b32 s9, s50, 7
	s_add_i32 s8, s8, s9
	s_ashr_i32 s9, s8, 31
	v_mul_f32_e32 v0, -0.5, v8
	s_mov_b32 s16, 0xc2fc0000
	s_lshl_b64 s[8:9], s[8:9], 1
	s_lshl_b32 s19, 1, s55
	v_cmp_gt_f32_e32 vcc, s16, v0
	v_mov_b32_e32 v5, v2
	s_and_b64 s[16:17], vcc, exec
	v_lshl_add_u64 v[2:3], v[4:5], 0, s[8:9]
	s_cselect_b32 s16, 0xffffffc0, 0
	s_add_u32 s8, s26, s8
	s_addc_u32 s9, s27, s9
	s_sub_i32 s17, 0x80, s56
	s_ashr_i32 s17, s17, 5
	s_cmp_lt_u32 s18, 4
	s_cselect_b32 s17, s17, 0
	s_lshl_b32 s18, s17, 5
	s_add_i32 s30, s56, s18
	s_add_i32 s51, s30, 0xffffff80
	v_add_u32_e32 v10, s51, v204
	v_max_i32_e32 v0, 0xffffffe4, v10
	v_lshl_add_u64 v[2:3], v[2:3], 0, v[182:183]
	v_add_u32_e32 v0, 28, v0
	v_lshlrev_b32_e32 v184, 1, v180
	v_mov_b32_e32 v185, v1
	v_lshlrev_b64 v[2:3], s55, v[0:1]
	v_lshl_add_u64 v[190:191], s[8:9], 0, v[184:185]
	v_lshl_add_u64 v[2:3], v[2:3], 0, s[10:11]
	v_lshl_add_u64 v[188:189], s[8:9], 0, v[182:183]
	v_or_b32_e32 v114, s56, v204
	v_mov_b32_e32 v115, v1
	v_lshlrev_b64 v[114:115], s55, v[114:115]
	v_lshl_add_u64 v[114:115], v[114:115], 0, s[10:11]
	v_mad_u64_u32 v[116:117], s[8:9], v114, s83, v[190:191]
	s_lshl_b32 s8, 4, s55
	s_mul_i32 s8, s8, s83
	s_mov_b32 s9, 0
	global_load_dwordx4 v[82:85], v[116:117], off
	v_lshl_add_u64 v[116:117], v[116:117], 0, s[8:9]
	global_load_dwordx4 v[86:89], v[116:117], off
	v_lshl_add_u64 v[116:117], v[116:117], 0, s[8:9]
	global_load_dwordx4 v[90:93], v[116:117], off
	v_lshl_add_u64 v[116:117], v[116:117], 0, s[8:9]
	global_load_dwordx4 v[94:97], v[116:117], off
	v_lshl_add_u64 v[116:117], v[116:117], 0, s[8:9]
	global_load_dwordx4 v[98:101], v[116:117], off
	v_lshl_add_u64 v[116:117], v[116:117], 0, s[8:9]
	global_load_dwordx4 v[102:105], v[116:117], off
	v_lshl_add_u64 v[116:117], v[116:117], 0, s[8:9]
	global_load_dwordx4 v[106:109], v[116:117], off
	v_lshl_add_u64 v[116:117], v[116:117], 0, s[8:9]
	global_load_dwordx4 v[110:113], v[116:117], off
	v_mad_u64_u32 v[4:5], s[8:9], v2, s83, v[190:191]
	v_mov_b32_e32 v0, v5
	v_mad_u64_u32 v[2:3], s[8:9], v3, s83, v[0:1]
	v_max_i32_e32 v0, 0xffffffe8, v10
	v_add_u32_e32 v0, 24, v0
	v_mov_b32_e32 v5, v2
	v_lshlrev_b64 v[2:3], s55, v[0:1]
	v_lshl_add_u64 v[2:3], v[2:3], 0, s[10:11]
	v_mad_u64_u32 v[6:7], s[8:9], v2, s83, v[190:191]
	v_mov_b32_e32 v0, v7
	v_mad_u64_u32 v[2:3], s[8:9], v3, s83, v[0:1]
	v_max_i32_e32 v0, 0xffffffec, v10
	v_add_u32_e32 v0, 20, v0
	v_mov_b32_e32 v7, v2
	v_lshlrev_b64 v[2:3], s55, v[0:1]
	v_lshl_add_u64 v[2:3], v[2:3], 0, s[10:11]
	global_load_dwordx4 v[142:145], v[4:5], off offset:768
	global_load_dwordx4 v[174:177], v[4:5], off offset:1536
	global_load_dwordx4 v[138:141], v[6:7], off offset:768
	global_load_dwordx4 v[170:173], v[6:7], off offset:1536
	v_mad_u64_u32 v[4:5], s[8:9], v2, s83, v[190:191]
	v_mov_b32_e32 v0, v5
	v_mad_u64_u32 v[2:3], s[8:9], v3, s83, v[0:1]
	v_max_i32_e32 v0, -16, v10
	v_add_u32_e32 v0, 16, v0
	v_mov_b32_e32 v5, v2
	v_lshlrev_b64 v[2:3], s55, v[0:1]
	v_lshl_add_u64 v[2:3], v[2:3], 0, s[10:11]
	v_mad_u64_u32 v[6:7], s[8:9], v2, s83, v[190:191]
	v_mov_b32_e32 v0, v7
	v_mad_u64_u32 v[2:3], s[8:9], v3, s83, v[0:1]
	v_max_i32_e32 v0, -12, v10
	v_add_u32_e32 v0, 12, v0
	v_mov_b32_e32 v7, v2
	v_lshlrev_b64 v[2:3], s55, v[0:1]
	v_lshl_add_u64 v[2:3], v[2:3], 0, s[10:11]
	global_load_dwordx4 v[134:137], v[4:5], off offset:768
	global_load_dwordx4 v[166:169], v[4:5], off offset:1536
	global_load_dwordx4 v[130:133], v[6:7], off offset:768
	global_load_dwordx4 v[162:165], v[6:7], off offset:1536
	v_mad_u64_u32 v[4:5], s[8:9], v2, s83, v[190:191]
	v_mov_b32_e32 v0, v5
	v_mad_u64_u32 v[2:3], s[8:9], v3, s83, v[0:1]
	v_max_i32_e32 v0, -8, v10
	v_add_u32_e32 v0, 8, v0
	v_mov_b32_e32 v5, v2
	v_lshlrev_b64 v[2:3], s55, v[0:1]
	v_lshl_add_u64 v[2:3], v[2:3], 0, s[10:11]
	v_mad_u64_u32 v[6:7], s[8:9], v2, s83, v[190:191]
	v_mov_b32_e32 v0, v7
	v_mad_u64_u32 v[2:3], s[8:9], v3, s83, v[0:1]
	v_max_i32_e32 v0, -4, v10
	v_add_u32_e32 v0, 4, v0
	v_mov_b32_e32 v7, v2
	v_lshlrev_b64 v[2:3], s55, v[0:1]
	v_lshl_add_u64 v[2:3], v[2:3], 0, s[10:11]
	global_load_dwordx4 v[126:129], v[4:5], off offset:768
	global_load_dwordx4 v[154:157], v[4:5], off offset:1536
	global_load_dwordx4 v[122:125], v[6:7], off offset:768
	global_load_dwordx4 v[158:161], v[6:7], off offset:1536
	v_mad_u64_u32 v[4:5], s[8:9], v2, s83, v[190:191]
	v_mov_b32_e32 v0, v5
	v_mad_u64_u32 v[2:3], s[8:9], v3, s83, v[0:1]
	v_max_i32_e32 v0, 0, v10
	v_mov_b32_e32 v5, v2
	v_lshlrev_b64 v[2:3], s55, v[0:1]
	v_lshl_add_u64 v[2:3], v[2:3], 0, s[10:11]
	v_mad_u64_u32 v[6:7], s[8:9], v2, s83, v[190:191]
	v_mov_b32_e32 v0, v7
	s_cmp_gt_i32 s51, -1
	v_cndmask_b32_e32 v9, 0, v201, vcc
	v_mad_u64_u32 v[2:3], s[8:9], v3, s83, v[0:1]
	v_or_b32_e32 v0, s51, v181
	s_cselect_b64 vcc, -1, 0
	v_mov_b32_e32 v7, v2
	v_cndmask_b32_e32 v2, 0, v0, vcc
	v_ashrrev_i32_e32 v3, 31, v2
	v_lshlrev_b64 v[2:3], s55, v[2:3]
	v_lshl_add_u64 v[2:3], v[2:3], 0, s[10:11]
	global_load_dwordx4 v[118:121], v[4:5], off offset:768
	global_load_dwordx4 v[146:149], v[4:5], off offset:1536
	global_load_dwordx4 v[114:117], v[6:7], off offset:768
	global_load_dwordx4 v[150:153], v[6:7], off offset:1536
	v_mad_u64_u32 v[4:5], s[8:9], v2, s83, v[188:189]
	v_mov_b32_e32 v0, v5
	v_mad_u64_u32 v[2:3], s[8:9], v3, s83, v[0:1]
	v_mov_b32_e32 v5, v2
	v_fmac_f32_e32 v9, -0.5, v8
	v_exp_f32_e32 v0, v9
	v_cvt_f32_u32_e32 v2, s19
	v_mov_b32_e32 v14, v1
	v_mov_b32_e32 v15, v1
	v_ldexp_f32 v0, v0, s16
	v_mul_f32_e32 v0, v0, v2
	v_mul_f32_e32 v185, 0x3fb8aa3b, v0
	v_mov_b32_e32 v0, v1
	v_mov_b32_e32 v2, v1
	v_mov_b32_e32 v3, v1
	v_mov_b32_e32 v4, v1
	v_mov_b32_e32 v5, v1
	v_mov_b32_e32 v6, v1
	v_mov_b32_e32 v7, v1
	v_mov_b32_e32 v8, v1
	v_mov_b32_e32 v9, v1
	v_mov_b32_e32 v10, v1
	v_mov_b32_e32 v11, v1
	v_mov_b32_e32 v12, v1
	v_mov_b32_e32 v13, v1
	v_mov_b64_e32 v[64:65], v[14:15]
	v_mov_b64_e32 v[48:49], v[14:15]
	v_mov_b64_e32 v[32:33], v[14:15]
	v_mov_b64_e32 v[62:63], v[12:13]
	v_mov_b64_e32 v[60:61], v[10:11]
	v_mov_b64_e32 v[58:59], v[8:9]
	v_mov_b64_e32 v[56:57], v[6:7]
	v_mov_b64_e32 v[54:55], v[4:5]
	v_mov_b64_e32 v[52:53], v[2:3]
	v_mov_b64_e32 v[50:51], v[0:1]
	v_mov_b64_e32 v[46:47], v[12:13]
	v_mov_b64_e32 v[44:45], v[10:11]
	v_mov_b64_e32 v[42:43], v[8:9]
	v_mov_b64_e32 v[40:41], v[6:7]
	v_mov_b64_e32 v[38:39], v[4:5]
	v_mov_b64_e32 v[36:37], v[2:3]
	v_mov_b64_e32 v[34:35], v[0:1]
	v_mov_b64_e32 v[30:31], v[12:13]
	v_mov_b64_e32 v[28:29], v[10:11]
	v_mov_b64_e32 v[26:27], v[8:9]
	v_mov_b64_e32 v[24:25], v[6:7]
	v_mov_b64_e32 v[22:23], v[4:5]
	v_mov_b64_e32 v[20:21], v[2:3]
	v_mov_b64_e32 v[18:19], v[0:1]
	v_mov_b64_e32 v[16:17], v[14:15]
	s_add_i32 s16, s17, -1
	v_subrev_u32_e32 v242, s18, v217
	v_mov_b32_e32 v243, 0
	v_mov_b32_e32 v244, 0xf149f2ca
	v_mov_b64_e32 v[14:15], v[12:13]
	v_mov_b64_e32 v[12:13], v[10:11]
	v_mov_b64_e32 v[10:11], v[8:9]
	v_mov_b64_e32 v[8:9], v[6:7]
	v_mov_b64_e32 v[6:7], v[4:5]
	v_mov_b64_e32 v[4:5], v[2:3]
	v_mov_b64_e32 v[2:3], v[0:1]
	s_waitcnt vmcnt(16)
	ds_write_b128 v197, v[82:85]
	ds_write_b128 v197, v[86:89] offset:1088
	ds_write_b128 v197, v[90:93] offset:2176
	ds_write_b128 v197, v[94:97] offset:3264
	ds_write_b128 v197, v[98:101] offset:8704
	ds_write_b128 v197, v[102:105] offset:9792
	ds_write_b128 v197, v[106:109] offset:10880
	ds_write_b128 v197, v[110:113] offset:11968
	s_waitcnt lgkmcnt(0)
	ds_read_b128 v[82:85], v198
	ds_read_b128 v[86:89], v198 offset:32
	ds_read_b128 v[90:93], v198 offset:64
	ds_read_b128 v[94:97], v198 offset:96
	ds_read_b128 v[98:101], v198 offset:128
	ds_read_b128 v[102:105], v198 offset:160
	ds_read_b128 v[106:109], v198 offset:192
	ds_read_b128 v[110:113], v198 offset:224
	s_waitcnt lgkmcnt(0)
